# residual-add epilogues (WO/down GEMMs): throwaway dword loads prefetch the second half's X lines while the first half is processed
# baseline (speedup 1.0000x reference)
; DEV void unpack8(const u32x4 v, float (&f)[8]) { f[0] = bflo(v.x); f[1] = bfhi(v.x); f[2] = bflo(v.y); f[3] = bfhi(v.y); f[4] = bflo(v.z); f[5] = bfhi(v.z); f[6] = bflo(v.w); f[7] = bfhi(v.w); }
; DEV u32x4 pack8(const float (&f)[8]) { u32x4 w; w.x = cvt_pk_bf16(f[0], f[1]); w.y = cvt_pk_bf16(f[2], f[3]); w.z = cvt_pk_bf16(f[4], f[5]); w.w = cvt_pk_bf16(f[6], f[7]); return w; }
;     DEV bool operator()(f32x4 (&acc)[2][2][4][2], const Unit& u, int wr, int wc, int fr, int fq) const {
;         const int row0 = u.pm * BM + wr * 64 + fr, col0 = u.pn * BM + wc * 32 + 8 * fq;
; #pragma unroll
;         for (int ai = 0; ai < 2; ++ai) {
;             u32x4 old[4][2];
; #pragma unroll
;             for (int m = 0; m < 4; ++m)
; #pragma unroll
;                 for (int bj = 0; bj < 2; ++bj) old[m][bj] = *(const u32x4*)(X + (size_t)(row0 + ai * HALF + m * 16) * 1024 + col0 + bj * HALF);
; #pragma unroll
;             for (int m = 0; m < 4; ++m)
; #pragma unroll
;                 for (int bj = 0; bj < 2; ++bj) { float v[8]; unpack8(old[m][bj], v);
; #pragma unroll
;                     for (int j = 0; j < 4; ++j) { v[j] += acc[ai][bj][m][0][j]; v[4 + j] += acc[ai][bj][m][1][j]; }
;                     *(u32x4*)(X + (size_t)(row0 + ai * HALF + m * 16) * 1024 + col0 + bj * HALF) = pack8(v); }
.LBB0_72:
	v_lshl_or_b32 v132, s64, 8, v187
	v_lshl_add_u32 v130, s80, 8, v171
	v_ashrrev_i32_e32 v133, 31, v132
	v_lshlrev_b64 v[164:165], 1, v[132:133]
	v_ashrrev_i32_e32 v131, 31, v130
	v_lshl_add_u64 v[166:167], s[18:19], 0, v[164:165]
	v_lshlrev_b64 v[168:169], 11, v[130:131]
	v_lshl_add_u64 v[132:133], v[166:167], 0, v[168:169]
	global_load_dwordx4 v[190:193], v[132:133], off
	global_load_dwordx4 v[194:197], v[132:133], off offset:256
	v_or_b32_e32 v132, 16, v130
	v_ashrrev_i32_e32 v133, 31, v132
	v_lshlrev_b64 v[184:185], 11, v[132:133]
	v_lshl_add_u64 v[132:133], v[166:167], 0, v[184:185]
	global_load_dwordx4 v[150:153], v[132:133], off
	global_load_dwordx4 v[146:149], v[132:133], off offset:256
	v_or_b32_e32 v132, 32, v130
	v_ashrrev_i32_e32 v133, 31, v132
	v_lshlrev_b64 v[182:183], 11, v[132:133]
	v_lshl_add_u64 v[132:133], v[166:167], 0, v[182:183]
	global_load_dwordx4 v[142:145], v[132:133], off
	global_load_dwordx4 v[134:137], v[132:133], off offset:256
	v_or_b32_e32 v130, 48, v130
	v_ashrrev_i32_e32 v131, 31, v130
	v_lshlrev_b64 v[180:181], 11, v[130:131]
	v_lshl_add_u64 v[130:131], v[166:167], 0, v[180:181]
	global_load_dwordx4 v[138:141], v[130:131], off
	s_nop 0
	global_load_dwordx4 v[130:133], v[130:131], off offset:256
	s_mov_b64 s[82:83], 0x40000
	s_mov_b64 s[84:85], 0x48000
	s_mov_b64 s[86:87], 0x50000
	s_mov_b64 s[4:5], 0x58000
	s_andn2_b64 vcc, exec, s[40:41]
	s_mov_b64 s[98:99], 0x40000
	v_lshl_add_u64 v[202:203], v[168:169], 0, s[98:99]
	v_lshl_add_u64 v[202:203], v[166:167], 0, v[202:203]
	s_mov_b64 s[98:99], 0x48000
	v_lshl_add_u64 v[204:205], v[168:169], 0, s[98:99]
	v_lshl_add_u64 v[204:205], v[166:167], 0, v[204:205]
	s_mov_b64 s[98:99], 0x50000
	v_lshl_add_u64 v[206:207], v[168:169], 0, s[98:99]
	v_lshl_add_u64 v[206:207], v[166:167], 0, v[206:207]
	s_mov_b64 s[98:99], 0x58000
	v_lshl_add_u64 v[208:209], v[168:169], 0, s[98:99]
	v_lshl_add_u64 v[208:209], v[166:167], 0, v[208:209]
	global_load_dword v201, v[202:203], off
	global_load_dword v201, v[202:203], off offset:256
	global_load_dword v201, v[204:205], off
	global_load_dword v201, v[204:205], off offset:256
	global_load_dword v201, v[206:207], off
	global_load_dword v201, v[206:207], off offset:256
	global_load_dword v201, v[208:209], off
	global_load_dword v201, v[208:209], off offset:256
	s_waitcnt vmcnt(8)
	v_lshlrev_b32_e32 v189, 16, v190
	v_and_b32_e32 v190, 0xffff0000, v190
	v_lshlrev_b32_e32 v198, 16, v191
	v_and_b32_e32 v191, 0xffff0000, v191
	v_lshlrev_b32_e32 v199, 16, v192
	v_and_b32_e32 v192, 0xffff0000, v192
	v_lshlrev_b32_e32 v200, 16, v193
	v_and_b32_e32 v193, 0xffff0000, v193
	v_add_f32_e32 v126, v126, v189
	v_add_f32_e32 v189, v122, v199
	v_add_f32_e32 v122, v127, v190
	v_add_f32_e32 v127, v123, v192
	v_add_f32_e32 v123, v128, v198
	v_add_f32_e32 v128, v124, v200
	v_add_f32_e32 v124, v129, v191
	v_add_f32_e32 v125, v125, v193
	v_cvt_pk_bf16_f32 v122, v126, v122
	v_cvt_pk_bf16_f32 v123, v123, v124
	v_cvt_pk_bf16_f32 v124, v189, v127
	v_lshl_add_u64 v[126:127], s[18:19], 0, v[168:169]
	v_cvt_pk_bf16_f32 v125, v128, v125
	v_lshl_add_u64 v[126:127], v[126:127], 0, v[164:165]
	global_store_dwordx4 v[126:127], v[122:125], off
	v_lshlrev_b32_e32 v128, 16, v196
	v_and_b32_e32 v129, 0xffff0000, v196
	v_lshlrev_b32_e32 v122, 16, v194
	v_and_b32_e32 v123, 0xffff0000, v194
	v_lshlrev_b32_e32 v124, 16, v195
	v_and_b32_e32 v125, 0xffff0000, v195
	v_lshlrev_b32_e32 v189, 16, v197
	v_and_b32_e32 v190, 0xffff0000, v197
	v_add_f32_e32 v118, v118, v122
	v_add_f32_e32 v122, v114, v128
	v_add_f32_e32 v114, v119, v123
	v_add_f32_e32 v119, v115, v129
	v_add_f32_e32 v115, v120, v124
	v_add_f32_e32 v120, v116, v189
	v_add_f32_e32 v116, v121, v125
	v_add_f32_e32 v117, v117, v190
	v_cvt_pk_bf16_f32 v114, v118, v114
	v_cvt_pk_bf16_f32 v115, v115, v116
	v_cvt_pk_bf16_f32 v116, v122, v119
	v_cvt_pk_bf16_f32 v117, v120, v117
	global_store_dwordx4 v[126:127], v[114:117], off offset:256
	v_lshlrev_b32_e32 v118, 16, v152
	v_and_b32_e32 v119, 0xffff0000, v152
	v_lshlrev_b32_e32 v114, 16, v150
	v_and_b32_e32 v115, 0xffff0000, v150
	v_lshlrev_b32_e32 v116, 16, v151
	v_and_b32_e32 v117, 0xffff0000, v151
	v_lshlrev_b32_e32 v120, 16, v153
	v_and_b32_e32 v121, 0xffff0000, v153
	v_add_f32_e32 v110, v110, v114
	v_add_f32_e32 v114, v106, v118
	v_add_f32_e32 v106, v111, v115
	v_add_f32_e32 v111, v107, v119
	v_add_f32_e32 v107, v112, v116
	v_add_f32_e32 v112, v108, v120
	v_add_f32_e32 v108, v113, v117
	v_add_f32_e32 v109, v109, v121
	v_cvt_pk_bf16_f32 v106, v110, v106
	v_cvt_pk_bf16_f32 v107, v107, v108
	v_cvt_pk_bf16_f32 v108, v114, v111
	v_lshl_add_u64 v[110:111], s[18:19], 0, v[184:185]
	v_cvt_pk_bf16_f32 v109, v112, v109
	v_lshl_add_u64 v[110:111], v[110:111], 0, v[164:165]
	global_store_dwordx4 v[110:111], v[106:109], off
	v_lshlrev_b32_e32 v112, 16, v148
	v_and_b32_e32 v113, 0xffff0000, v148
	v_lshlrev_b32_e32 v106, 16, v146
	v_and_b32_e32 v107, 0xffff0000, v146
	v_lshlrev_b32_e32 v108, 16, v147
	v_and_b32_e32 v109, 0xffff0000, v147
	v_lshlrev_b32_e32 v114, 16, v149
	v_and_b32_e32 v115, 0xffff0000, v149
	v_add_f32_e32 v102, v102, v106
	v_add_f32_e32 v106, v94, v112
	v_add_f32_e32 v94, v103, v107
	v_add_f32_e32 v103, v95, v113
	v_add_f32_e32 v95, v104, v108
	v_add_f32_e32 v104, v96, v114
	v_add_f32_e32 v96, v105, v109
	v_add_f32_e32 v97, v97, v115
	v_cvt_pk_bf16_f32 v94, v102, v94
	v_cvt_pk_bf16_f32 v95, v95, v96
	v_cvt_pk_bf16_f32 v96, v106, v103
	v_cvt_pk_bf16_f32 v97, v104, v97
	global_store_dwordx4 v[110:111], v[94:97], off offset:256
	v_lshlrev_b32_e32 v102, 16, v144
	v_and_b32_e32 v103, 0xffff0000, v144
	v_lshlrev_b32_e32 v94, 16, v142
	v_and_b32_e32 v95, 0xffff0000, v142
; DEV void unpack8(const u32x4 v, float (&f)[8]) { f[0] = bflo(v.x); f[1] = bfhi(v.x); f[2] = bflo(v.y); f[3] = bfhi(v.y); f[4] = bflo(v.z); f[5] = bfhi(v.z); f[6] = bflo(v.w); f[7] = bfhi(v.w); }
; DEV u32x4 pack8(const float (&f)[8]) { u32x4 w; w.x = cvt_pk_bf16(f[0], f[1]); w.y = cvt_pk_bf16(f[2], f[3]); w.z = cvt_pk_bf16(f[4], f[5]); w.w = cvt_pk_bf16(f[6], f[7]); return w; }
;     DEV bool operator()(f32x4 (&acc)[2][2][4][2], const Unit& u, int wr, int wc, int fr, int fq) const {
;     ...
;         for (int ai = 0; ai < 2; ++ai) {
;             u32x4 old[4][2];
; #pragma unroll
;             for (int m = 0; m < 4; ++m)
; #pragma unroll
;                 for (int bj = 0; bj < 2; ++bj) old[m][bj] = *(const u32x4*)(X + (size_t)(row0 + ai * HALF + m * 16) * 1024 + col0 + bj * HALF);
; #pragma unroll
;             for (int m = 0; m < 4; ++m)
; #pragma unroll
;                 for (int bj = 0; bj < 2; ++bj) { float v[8]; unpack8(old[m][bj], v);
; #pragma unroll
;                     for (int j = 0; j < 4; ++j) { v[j] += acc[ai][bj][m][0][j]; v[4 + j] += acc[ai][bj][m][1][j]; }
;                     *(u32x4*)(X + (size_t)(row0 + ai * HALF + m * 16) * 1024 + col0 + bj * HALF) = pack8(v); }
	v_lshlrev_b32_e32 v96, 16, v143
	v_and_b32_e32 v97, 0xffff0000, v143
	v_lshlrev_b32_e32 v104, 16, v145
	v_and_b32_e32 v105, 0xffff0000, v145
	v_add_f32_e32 v94, v98, v94
	v_add_f32_e32 v98, v90, v102
	v_add_f32_e32 v90, v99, v95
	v_add_f32_e32 v95, v91, v103
	v_add_f32_e32 v91, v100, v96
	v_add_f32_e32 v96, v92, v104
	v_add_f32_e32 v92, v101, v97
	v_add_f32_e32 v93, v93, v105
	v_cvt_pk_bf16_f32 v90, v94, v90
	v_cvt_pk_bf16_f32 v91, v91, v92
	v_cvt_pk_bf16_f32 v92, v98, v95
	v_lshl_add_u64 v[94:95], s[18:19], 0, v[182:183]
	v_cvt_pk_bf16_f32 v93, v96, v93
	v_lshl_add_u64 v[94:95], v[94:95], 0, v[164:165]
	global_store_dwordx4 v[94:95], v[90:93], off
	v_lshlrev_b32_e32 v96, 16, v136
	v_and_b32_e32 v97, 0xffff0000, v136
	v_lshlrev_b32_e32 v90, 16, v134
	v_and_b32_e32 v91, 0xffff0000, v134
	v_lshlrev_b32_e32 v92, 16, v135
	v_and_b32_e32 v93, 0xffff0000, v135
	v_lshlrev_b32_e32 v98, 16, v137
	v_and_b32_e32 v99, 0xffff0000, v137
	v_add_f32_e32 v86, v86, v90
	v_add_f32_e32 v90, v78, v96
	v_add_f32_e32 v78, v87, v91
	v_add_f32_e32 v87, v79, v97
	v_add_f32_e32 v79, v88, v92
	v_add_f32_e32 v88, v80, v98
	v_add_f32_e32 v80, v89, v93
	v_add_f32_e32 v81, v81, v99
	v_cvt_pk_bf16_f32 v78, v86, v78
	v_cvt_pk_bf16_f32 v79, v79, v80
	v_cvt_pk_bf16_f32 v80, v90, v87
	v_cvt_pk_bf16_f32 v81, v88, v81
	global_store_dwordx4 v[94:95], v[78:81], off offset:256
	v_lshlrev_b32_e32 v86, 16, v140
	v_and_b32_e32 v87, 0xffff0000, v140
	v_lshlrev_b32_e32 v78, 16, v138
	v_and_b32_e32 v79, 0xffff0000, v138
	v_lshlrev_b32_e32 v80, 16, v139
	v_and_b32_e32 v81, 0xffff0000, v139
	v_lshlrev_b32_e32 v88, 16, v141
	v_and_b32_e32 v89, 0xffff0000, v141
	v_add_f32_e32 v78, v82, v78
	v_add_f32_e32 v82, v74, v86
	v_add_f32_e32 v74, v83, v79
	v_add_f32_e32 v79, v75, v87
	v_add_f32_e32 v75, v84, v80
	v_add_f32_e32 v80, v76, v88
	v_add_f32_e32 v76, v85, v81
	v_add_f32_e32 v77, v77, v89
	v_cvt_pk_bf16_f32 v74, v78, v74
	v_cvt_pk_bf16_f32 v75, v75, v76
	v_cvt_pk_bf16_f32 v76, v82, v79
	v_lshl_add_u64 v[78:79], s[18:19], 0, v[180:181]
	v_cvt_pk_bf16_f32 v77, v80, v77
	v_lshl_add_u64 v[78:79], v[78:79], 0, v[164:165]
	global_store_dwordx4 v[78:79], v[74:77], off
	v_lshlrev_b32_e32 v80, 16, v132
	v_and_b32_e32 v81, 0xffff0000, v132
	v_lshlrev_b32_e32 v74, 16, v130
	v_and_b32_e32 v75, 0xffff0000, v130
	v_lshlrev_b32_e32 v76, 16, v131
	v_and_b32_e32 v77, 0xffff0000, v131
	v_lshlrev_b32_e32 v82, 16, v133
	v_and_b32_e32 v83, 0xffff0000, v133
	v_add_f32_e32 v70, v70, v74
	v_add_f32_e32 v74, v66, v80
	v_add_f32_e32 v66, v71, v75
	v_add_f32_e32 v71, v67, v81
	v_add_f32_e32 v67, v72, v76
	v_add_f32_e32 v72, v68, v82
	v_add_f32_e32 v68, v73, v77
	v_add_f32_e32 v69, v69, v83
	v_lshl_add_u64 v[98:99], v[168:169], 0, s[82:83]
	v_cvt_pk_bf16_f32 v66, v70, v66
	v_cvt_pk_bf16_f32 v67, v67, v68
	v_cvt_pk_bf16_f32 v68, v74, v71
	v_cvt_pk_bf16_f32 v69, v72, v69
	global_store_dwordx4 v[78:79], v[66:69], off offset:256
	v_lshl_add_u64 v[70:71], v[166:167], 0, v[98:99]
	global_load_dwordx4 v[66:69], v[70:71], off
	s_nop 0
	global_load_dwordx4 v[70:73], v[70:71], off offset:256
	v_lshl_add_u64 v[100:101], v[168:169], 0, s[84:85]
	v_lshl_add_u64 v[78:79], v[166:167], 0, v[100:101]
	global_load_dwordx4 v[74:77], v[78:79], off
	s_nop 0
	global_load_dwordx4 v[78:81], v[78:79], off offset:256
	v_lshl_add_u64 v[102:103], v[168:169], 0, s[86:87]
	v_lshl_add_u64 v[86:87], v[166:167], 0, v[102:103]
	global_load_dwordx4 v[82:85], v[86:87], off
	s_nop 0
	global_load_dwordx4 v[86:89], v[86:87], off offset:256
	v_lshl_add_u64 v[104:105], v[168:169], 0, s[4:5]
	v_lshl_add_u64 v[94:95], v[166:167], 0, v[104:105]
	global_load_dwordx4 v[90:93], v[94:95], off
	s_nop 0
	global_load_dwordx4 v[94:97], v[94:95], off offset:256
	s_mov_b64 s[4:5], -1
	s_waitcnt vmcnt(7)
	v_lshlrev_b32_e32 v106, 16, v66
	v_and_b32_e32 v66, 0xffff0000, v66
	v_lshlrev_b32_e32 v107, 16, v67
	v_and_b32_e32 v67, 0xffff0000, v67
	v_lshlrev_b32_e32 v108, 16, v68
	v_and_b32_e32 v68, 0xffff0000, v68
	v_lshlrev_b32_e32 v109, 16, v69
	v_and_b32_e32 v69, 0xffff0000, v69
	v_add_f32_e32 v62, v62, v106
	v_add_f32_e32 v106, v58, v108
	v_add_f32_e32 v58, v63, v66
	v_add_f32_e32 v63, v59, v68
	v_add_f32_e32 v59, v64, v107
	v_add_f32_e32 v64, v60, v109
	v_add_f32_e32 v60, v65, v67
	v_add_f32_e32 v61, v61, v69
	v_cvt_pk_bf16_f32 v58, v62, v58
	v_cvt_pk_bf16_f32 v59, v59, v60
	v_cvt_pk_bf16_f32 v60, v106, v63
	v_lshl_add_u64 v[62:63], s[18:19], 0, v[98:99]
	v_cvt_pk_bf16_f32 v61, v64, v61
	v_lshl_add_u64 v[62:63], v[62:63], 0, v[164:165]
	global_store_dwordx4 v[62:63], v[58:61], off
	s_waitcnt vmcnt(7)
	v_lshlrev_b32_e32 v64, 16, v72
	v_and_b32_e32 v65, 0xffff0000, v72
	v_lshlrev_b32_e32 v58, 16, v70
	v_and_b32_e32 v59, 0xffff0000, v70
	v_lshlrev_b32_e32 v60, 16, v71
	v_and_b32_e32 v61, 0xffff0000, v71
	v_lshlrev_b32_e32 v66, 16, v73
	v_and_b32_e32 v67, 0xffff0000, v73
	v_add_f32_e32 v54, v54, v58
	v_add_f32_e32 v58, v46, v64
	v_add_f32_e32 v46, v55, v59
	v_add_f32_e32 v55, v47, v65
	v_add_f32_e32 v47, v56, v60
	v_add_f32_e32 v56, v48, v66
	v_add_f32_e32 v48, v57, v61
	v_add_f32_e32 v49, v49, v67
	v_cvt_pk_bf16_f32 v46, v54, v46
	v_cvt_pk_bf16_f32 v47, v47, v48
	v_cvt_pk_bf16_f32 v48, v58, v55
	v_cvt_pk_bf16_f32 v49, v56, v49
	global_store_dwordx4 v[62:63], v[46:49], off offset:256
	s_waitcnt vmcnt(7)
; DEV void unpack8(const u32x4 v, float (&f)[8]) { f[0] = bflo(v.x); f[1] = bfhi(v.x); f[2] = bflo(v.y); f[3] = bfhi(v.y); f[4] = bflo(v.z); f[5] = bfhi(v.z); f[6] = bflo(v.w); f[7] = bfhi(v.w); }
; DEV u32x4 pack8(const float (&f)[8]) { u32x4 w; w.x = cvt_pk_bf16(f[0], f[1]); w.y = cvt_pk_bf16(f[2], f[3]); w.z = cvt_pk_bf16(f[4], f[5]); w.w = cvt_pk_bf16(f[6], f[7]); return w; }
; #define PG8_BAR __builtin_amdgcn_s_barrier()
;     DEV bool operator()(f32x4 (&acc)[2][2][4][2], const Unit& u, int wr, int wc, int fr, int fq) const {
;     ...
;             for (int m = 0; m < 4; ++m)
; #pragma unroll
;                 for (int bj = 0; bj < 2; ++bj) { float v[8]; unpack8(old[m][bj], v);
; #pragma unroll
;                     for (int j = 0; j < 4; ++j) { v[j] += acc[ai][bj][m][0][j]; v[4 + j] += acc[ai][bj][m][1][j]; }
;                     *(u32x4*)(X + (size_t)(row0 + ai * HALF + m * 16) * 1024 + col0 + bj * HALF) = pack8(v); }
; template <bool ALIGN_EPI, class Epi, class Sched>
; DEV void gemm_phase(LAS unsigned char* lds, const Gemm g, const Sched& S, const Epi& E) {
;     ...
;         if (!has_next) break;
;         if (rst) {
; #pragma unroll
;         for (int a = 0; a < 2; ++a)
; #pragma unroll
;             for (int b = 0; b < 2; ++b)
; #pragma unroll
;                 for (int m = 0; m < 4; ++m)
; #pragma unroll
;                     for (int n = 0; n < 2; ++n) acc[a][b][m][n] = (f32x4){0.f, 0.f, 0.f, 0.f}; }
;         cur = nxt; cA = nA; cB = nB; ++ui;
;         if (ALIGN_EPI) { if (wr == 1) PG8_BAR; }
	v_lshlrev_b32_e32 v54, 16, v76
	v_and_b32_e32 v55, 0xffff0000, v76
	v_lshlrev_b32_e32 v46, 16, v74
	v_and_b32_e32 v47, 0xffff0000, v74
	v_lshlrev_b32_e32 v48, 16, v75
	v_and_b32_e32 v49, 0xffff0000, v75
	v_lshlrev_b32_e32 v56, 16, v77
	v_and_b32_e32 v57, 0xffff0000, v77
	v_add_f32_e32 v46, v50, v46
	v_add_f32_e32 v50, v42, v54
	v_add_f32_e32 v42, v51, v47
	v_add_f32_e32 v47, v43, v55
	v_add_f32_e32 v43, v52, v48
	v_add_f32_e32 v48, v44, v56
	v_add_f32_e32 v44, v53, v49
	v_add_f32_e32 v45, v45, v57
	v_cvt_pk_bf16_f32 v42, v46, v42
	v_cvt_pk_bf16_f32 v43, v43, v44
	v_cvt_pk_bf16_f32 v44, v50, v47
	v_lshl_add_u64 v[46:47], s[18:19], 0, v[100:101]
	v_cvt_pk_bf16_f32 v45, v48, v45
	v_lshl_add_u64 v[46:47], v[46:47], 0, v[164:165]
	global_store_dwordx4 v[46:47], v[42:45], off
	s_waitcnt vmcnt(7)
	v_lshlrev_b32_e32 v48, 16, v80
	v_and_b32_e32 v49, 0xffff0000, v80
	v_lshlrev_b32_e32 v42, 16, v78
	v_and_b32_e32 v43, 0xffff0000, v78
	v_lshlrev_b32_e32 v44, 16, v79
	v_and_b32_e32 v45, 0xffff0000, v79
	v_lshlrev_b32_e32 v50, 16, v81
	v_and_b32_e32 v51, 0xffff0000, v81
	v_add_f32_e32 v38, v38, v42
	v_add_f32_e32 v42, v30, v48
	v_add_f32_e32 v30, v39, v43
	v_add_f32_e32 v39, v31, v49
	v_add_f32_e32 v31, v40, v44
	v_add_f32_e32 v40, v32, v50
	v_add_f32_e32 v32, v41, v45
	v_add_f32_e32 v33, v33, v51
	v_cvt_pk_bf16_f32 v30, v38, v30
	v_cvt_pk_bf16_f32 v31, v31, v32
	v_cvt_pk_bf16_f32 v32, v42, v39
	v_cvt_pk_bf16_f32 v33, v40, v33
	global_store_dwordx4 v[46:47], v[30:33], off offset:256
	s_waitcnt vmcnt(7)
	v_lshlrev_b32_e32 v38, 16, v84
	v_and_b32_e32 v39, 0xffff0000, v84
	v_lshlrev_b32_e32 v30, 16, v82
	v_and_b32_e32 v31, 0xffff0000, v82
	v_lshlrev_b32_e32 v32, 16, v83
	v_and_b32_e32 v33, 0xffff0000, v83
	v_lshlrev_b32_e32 v40, 16, v85
	v_and_b32_e32 v41, 0xffff0000, v85
	v_add_f32_e32 v30, v34, v30
	v_add_f32_e32 v34, v26, v38
	v_add_f32_e32 v26, v35, v31
	v_add_f32_e32 v31, v27, v39
	v_add_f32_e32 v27, v36, v32
	v_add_f32_e32 v32, v28, v40
	v_add_f32_e32 v28, v37, v33
	v_add_f32_e32 v29, v29, v41
	v_cvt_pk_bf16_f32 v26, v30, v26
	v_cvt_pk_bf16_f32 v27, v27, v28
	v_cvt_pk_bf16_f32 v28, v34, v31
	v_lshl_add_u64 v[30:31], s[18:19], 0, v[102:103]
	v_cvt_pk_bf16_f32 v29, v32, v29
	v_lshl_add_u64 v[30:31], v[30:31], 0, v[164:165]
	global_store_dwordx4 v[30:31], v[26:29], off
	s_waitcnt vmcnt(7)
	v_lshlrev_b32_e32 v32, 16, v88
	v_and_b32_e32 v33, 0xffff0000, v88
	v_lshlrev_b32_e32 v26, 16, v86
	v_and_b32_e32 v27, 0xffff0000, v86
	v_lshlrev_b32_e32 v28, 16, v87
	v_and_b32_e32 v29, 0xffff0000, v87
	v_lshlrev_b32_e32 v34, 16, v89
	v_and_b32_e32 v35, 0xffff0000, v89
	v_add_f32_e32 v22, v22, v26
	v_add_f32_e32 v26, v14, v32
	v_add_f32_e32 v14, v23, v27
	v_add_f32_e32 v23, v15, v33
	v_add_f32_e32 v15, v24, v28
	v_add_f32_e32 v24, v16, v34
	v_add_f32_e32 v16, v25, v29
	v_add_f32_e32 v17, v17, v35
	v_cvt_pk_bf16_f32 v14, v22, v14
	v_cvt_pk_bf16_f32 v15, v15, v16
	v_cvt_pk_bf16_f32 v16, v26, v23
	v_cvt_pk_bf16_f32 v17, v24, v17
	global_store_dwordx4 v[30:31], v[14:17], off offset:256
	s_waitcnt vmcnt(7)
	v_lshlrev_b32_e32 v22, 16, v92
	v_and_b32_e32 v23, 0xffff0000, v92
	v_lshlrev_b32_e32 v14, 16, v90
	v_and_b32_e32 v15, 0xffff0000, v90
	v_lshlrev_b32_e32 v16, 16, v91
	v_and_b32_e32 v17, 0xffff0000, v91
	v_lshlrev_b32_e32 v24, 16, v93
	v_and_b32_e32 v25, 0xffff0000, v93
	v_add_f32_e32 v14, v18, v14
	v_add_f32_e32 v18, v10, v22
	v_add_f32_e32 v10, v19, v15
	v_add_f32_e32 v15, v11, v23
	v_add_f32_e32 v11, v20, v16
	v_add_f32_e32 v16, v12, v24
	v_add_f32_e32 v12, v21, v17
	v_add_f32_e32 v13, v13, v25
	v_cvt_pk_bf16_f32 v10, v14, v10
	v_cvt_pk_bf16_f32 v11, v11, v12
	v_cvt_pk_bf16_f32 v12, v18, v15
	v_lshl_add_u64 v[14:15], s[18:19], 0, v[104:105]
	v_cvt_pk_bf16_f32 v13, v16, v13
	v_lshl_add_u64 v[14:15], v[14:15], 0, v[164:165]
	global_store_dwordx4 v[14:15], v[10:13], off
	s_waitcnt vmcnt(7)
	v_lshlrev_b32_e32 v16, 16, v96
	v_and_b32_e32 v17, 0xffff0000, v96
	v_lshlrev_b32_e32 v10, 16, v94
	v_and_b32_e32 v11, 0xffff0000, v94
	v_lshlrev_b32_e32 v12, 16, v95
	v_and_b32_e32 v13, 0xffff0000, v95
	v_lshlrev_b32_e32 v18, 16, v97
	v_and_b32_e32 v19, 0xffff0000, v97
	v_add_f32_e32 v6, v6, v10
	v_add_f32_e32 v10, v2, v16
	v_add_f32_e32 v2, v7, v11
	v_add_f32_e32 v7, v3, v17
	v_add_f32_e32 v3, v8, v12
	v_add_f32_e32 v8, v4, v18
	v_add_f32_e32 v4, v9, v13
	v_add_f32_e32 v5, v5, v19
	v_cvt_pk_bf16_f32 v2, v6, v2
	v_cvt_pk_bf16_f32 v3, v3, v4
	v_cvt_pk_bf16_f32 v4, v10, v7
	v_cvt_pk_bf16_f32 v5, v8, v5
	global_store_dwordx4 v[14:15], v[2:5], off offset:256
	s_cbranch_vccnz .LBB0_61
	s_andn2_b64 vcc, exec, s[42:43]
	s_cbranch_vccnz .LBB0_60
	s_barrier
	s_branch .LBB0_60

; DEV void unpack8(const u32x4 v, float (&f)[8]) { f[0] = bflo(v.x); f[1] = bfhi(v.x); f[2] = bflo(v.y); f[3] = bfhi(v.y); f[4] = bflo(v.z); f[5] = bfhi(v.z); f[6] = bflo(v.w); f[7] = bfhi(v.w); }
; DEV u32x4 pack8(const float (&f)[8]) { u32x4 w; w.x = cvt_pk_bf16(f[0], f[1]); w.y = cvt_pk_bf16(f[2], f[3]); w.z = cvt_pk_bf16(f[4], f[5]); w.w = cvt_pk_bf16(f[6], f[7]); return w; }
;     DEV bool operator()(f32x4 (&acc)[2][2][4][2], const Unit& u, int wr, int wc, int fr, int fq) const {
;         const int row0 = u.pm * BM + wr * 64 + fr, col0 = u.pn * BM + wc * 32 + 8 * fq;
; #pragma unroll
;         for (int ai = 0; ai < 2; ++ai) {
;             u32x4 old[4][2];
; #pragma unroll
;             for (int m = 0; m < 4; ++m)
; #pragma unroll
;                 for (int bj = 0; bj < 2; ++bj) old[m][bj] = *(const u32x4*)(X + (size_t)(row0 + ai * HALF + m * 16) * 1024 + col0 + bj * HALF);
; #pragma unroll
;             for (int m = 0; m < 4; ++m)
; #pragma unroll
;                 for (int bj = 0; bj < 2; ++bj) { float v[8]; unpack8(old[m][bj], v);
; #pragma unroll
;                     for (int j = 0; j < 4; ++j) { v[j] += acc[ai][bj][m][0][j]; v[4 + j] += acc[ai][bj][m][1][j]; }
;                     *(u32x4*)(X + (size_t)(row0 + ai * HALF + m * 16) * 1024 + col0 + bj * HALF) = pack8(v); }
.LBB0_491:
	v_lshl_or_b32 v132, s64, 8, v187
	v_lshl_add_u32 v130, s77, 8, v171
	v_ashrrev_i32_e32 v133, 31, v132
	v_lshlrev_b64 v[164:165], 1, v[132:133]
	v_ashrrev_i32_e32 v131, 31, v130
	v_lshl_add_u64 v[166:167], s[18:19], 0, v[164:165]
	v_lshlrev_b64 v[168:169], 11, v[130:131]
	v_lshl_add_u64 v[132:133], v[166:167], 0, v[168:169]
	global_load_dwordx4 v[190:193], v[132:133], off
	global_load_dwordx4 v[194:197], v[132:133], off offset:256
	v_or_b32_e32 v132, 16, v130
	v_ashrrev_i32_e32 v133, 31, v132
	v_lshlrev_b64 v[184:185], 11, v[132:133]
	v_lshl_add_u64 v[132:133], v[166:167], 0, v[184:185]
	global_load_dwordx4 v[150:153], v[132:133], off
	global_load_dwordx4 v[146:149], v[132:133], off offset:256
	v_or_b32_e32 v132, 32, v130
	v_ashrrev_i32_e32 v133, 31, v132
	v_lshlrev_b64 v[182:183], 11, v[132:133]
	v_lshl_add_u64 v[132:133], v[166:167], 0, v[182:183]
	global_load_dwordx4 v[142:145], v[132:133], off
	global_load_dwordx4 v[134:137], v[132:133], off offset:256
	v_or_b32_e32 v130, 48, v130
	v_ashrrev_i32_e32 v131, 31, v130
	v_lshlrev_b64 v[180:181], 11, v[130:131]
	v_lshl_add_u64 v[130:131], v[166:167], 0, v[180:181]
	global_load_dwordx4 v[138:141], v[130:131], off
	s_nop 0
	global_load_dwordx4 v[130:133], v[130:131], off offset:256
	s_mov_b64 s[4:5], 0x58000
	s_and_b64 vcc, exec, s[40:41]
	s_mov_b64 s[98:99], 0x40000
	v_lshl_add_u64 v[202:203], v[168:169], 0, s[98:99]
	v_lshl_add_u64 v[202:203], v[166:167], 0, v[202:203]
	s_mov_b64 s[98:99], 0x48000
	v_lshl_add_u64 v[204:205], v[168:169], 0, s[98:99]
	v_lshl_add_u64 v[204:205], v[166:167], 0, v[204:205]
	s_mov_b64 s[98:99], 0x50000
	v_lshl_add_u64 v[206:207], v[168:169], 0, s[98:99]
	v_lshl_add_u64 v[206:207], v[166:167], 0, v[206:207]
	s_mov_b64 s[98:99], 0x58000
	v_lshl_add_u64 v[208:209], v[168:169], 0, s[98:99]
	v_lshl_add_u64 v[208:209], v[166:167], 0, v[208:209]
	global_load_dword v201, v[202:203], off
	global_load_dword v201, v[202:203], off offset:256
	global_load_dword v201, v[204:205], off
	global_load_dword v201, v[204:205], off offset:256
	global_load_dword v201, v[206:207], off
	global_load_dword v201, v[206:207], off offset:256
	global_load_dword v201, v[208:209], off
	global_load_dword v201, v[208:209], off offset:256
	s_waitcnt vmcnt(8)
	v_lshlrev_b32_e32 v189, 16, v190
	v_and_b32_e32 v190, 0xffff0000, v190
	v_lshlrev_b32_e32 v198, 16, v191
	v_and_b32_e32 v191, 0xffff0000, v191
	v_lshlrev_b32_e32 v199, 16, v192
	v_and_b32_e32 v192, 0xffff0000, v192
	v_lshlrev_b32_e32 v200, 16, v193
	v_and_b32_e32 v193, 0xffff0000, v193
	v_add_f32_e32 v126, v126, v189
	v_add_f32_e32 v189, v122, v199
	v_add_f32_e32 v122, v127, v190
	v_add_f32_e32 v127, v123, v192
	v_add_f32_e32 v123, v128, v198
	v_add_f32_e32 v128, v124, v200
	v_add_f32_e32 v124, v129, v191
	v_add_f32_e32 v125, v125, v193
	v_cvt_pk_bf16_f32 v122, v126, v122
	v_cvt_pk_bf16_f32 v123, v123, v124
	v_cvt_pk_bf16_f32 v124, v189, v127
	v_lshl_add_u64 v[126:127], s[18:19], 0, v[168:169]
	v_cvt_pk_bf16_f32 v125, v128, v125
	v_lshl_add_u64 v[126:127], v[126:127], 0, v[164:165]
	global_store_dwordx4 v[126:127], v[122:125], off
	v_lshlrev_b32_e32 v128, 16, v196
	v_and_b32_e32 v129, 0xffff0000, v196
	v_lshlrev_b32_e32 v122, 16, v194
	v_and_b32_e32 v123, 0xffff0000, v194
	v_lshlrev_b32_e32 v124, 16, v195
	v_and_b32_e32 v125, 0xffff0000, v195
	v_lshlrev_b32_e32 v189, 16, v197
	v_and_b32_e32 v190, 0xffff0000, v197
	v_add_f32_e32 v118, v118, v122
	v_add_f32_e32 v122, v114, v128
	v_add_f32_e32 v114, v119, v123
	v_add_f32_e32 v119, v115, v129
	v_add_f32_e32 v115, v120, v124
	v_add_f32_e32 v120, v116, v189
	v_add_f32_e32 v116, v121, v125
	v_add_f32_e32 v117, v117, v190
	v_cvt_pk_bf16_f32 v114, v118, v114
	v_cvt_pk_bf16_f32 v115, v115, v116
	v_cvt_pk_bf16_f32 v116, v122, v119
	v_cvt_pk_bf16_f32 v117, v120, v117
	global_store_dwordx4 v[126:127], v[114:117], off offset:256
	v_lshlrev_b32_e32 v118, 16, v152
	v_and_b32_e32 v119, 0xffff0000, v152
	v_lshlrev_b32_e32 v114, 16, v150
	v_and_b32_e32 v115, 0xffff0000, v150
	v_lshlrev_b32_e32 v116, 16, v151
	v_and_b32_e32 v117, 0xffff0000, v151
	v_lshlrev_b32_e32 v120, 16, v153
	v_and_b32_e32 v121, 0xffff0000, v153
	v_add_f32_e32 v110, v110, v114
	v_add_f32_e32 v114, v106, v118
	v_add_f32_e32 v106, v111, v115
	v_add_f32_e32 v111, v107, v119
	v_add_f32_e32 v107, v112, v116
	v_add_f32_e32 v112, v108, v120
	v_add_f32_e32 v108, v113, v117
	v_add_f32_e32 v109, v109, v121
	v_cvt_pk_bf16_f32 v106, v110, v106
	v_cvt_pk_bf16_f32 v107, v107, v108
	v_cvt_pk_bf16_f32 v108, v114, v111
	v_lshl_add_u64 v[110:111], s[18:19], 0, v[184:185]
	v_cvt_pk_bf16_f32 v109, v112, v109
	v_lshl_add_u64 v[110:111], v[110:111], 0, v[164:165]
	global_store_dwordx4 v[110:111], v[106:109], off
	v_lshlrev_b32_e32 v112, 16, v148
	v_and_b32_e32 v113, 0xffff0000, v148
	v_lshlrev_b32_e32 v106, 16, v146
	v_and_b32_e32 v107, 0xffff0000, v146
	v_lshlrev_b32_e32 v108, 16, v147
	v_and_b32_e32 v109, 0xffff0000, v147
	v_lshlrev_b32_e32 v114, 16, v149
	v_and_b32_e32 v115, 0xffff0000, v149
	v_add_f32_e32 v102, v102, v106
	v_add_f32_e32 v106, v94, v112
	v_add_f32_e32 v94, v103, v107
	v_add_f32_e32 v103, v95, v113
	v_add_f32_e32 v95, v104, v108
	v_add_f32_e32 v104, v96, v114
	v_add_f32_e32 v96, v105, v109
	v_add_f32_e32 v97, v97, v115
	v_cvt_pk_bf16_f32 v94, v102, v94
	v_cvt_pk_bf16_f32 v95, v95, v96
	v_cvt_pk_bf16_f32 v96, v106, v103
	v_cvt_pk_bf16_f32 v97, v104, v97
	global_store_dwordx4 v[110:111], v[94:97], off offset:256
	v_lshlrev_b32_e32 v102, 16, v144
	v_and_b32_e32 v103, 0xffff0000, v144
	v_lshlrev_b32_e32 v94, 16, v142
	v_and_b32_e32 v95, 0xffff0000, v142
	v_lshlrev_b32_e32 v96, 16, v143
	v_and_b32_e32 v97, 0xffff0000, v143
; DEV void unpack8(const u32x4 v, float (&f)[8]) { f[0] = bflo(v.x); f[1] = bfhi(v.x); f[2] = bflo(v.y); f[3] = bfhi(v.y); f[4] = bflo(v.z); f[5] = bfhi(v.z); f[6] = bflo(v.w); f[7] = bfhi(v.w); }
; DEV u32x4 pack8(const float (&f)[8]) { u32x4 w; w.x = cvt_pk_bf16(f[0], f[1]); w.y = cvt_pk_bf16(f[2], f[3]); w.z = cvt_pk_bf16(f[4], f[5]); w.w = cvt_pk_bf16(f[6], f[7]); return w; }
;     DEV bool operator()(f32x4 (&acc)[2][2][4][2], const Unit& u, int wr, int wc, int fr, int fq) const {
;     ...
;         for (int ai = 0; ai < 2; ++ai) {
;             u32x4 old[4][2];
; #pragma unroll
;             for (int m = 0; m < 4; ++m)
; #pragma unroll
;                 for (int bj = 0; bj < 2; ++bj) old[m][bj] = *(const u32x4*)(X + (size_t)(row0 + ai * HALF + m * 16) * 1024 + col0 + bj * HALF);
; #pragma unroll
;             for (int m = 0; m < 4; ++m)
; #pragma unroll
;                 for (int bj = 0; bj < 2; ++bj) { float v[8]; unpack8(old[m][bj], v);
; #pragma unroll
;                     for (int j = 0; j < 4; ++j) { v[j] += acc[ai][bj][m][0][j]; v[4 + j] += acc[ai][bj][m][1][j]; }
;                     *(u32x4*)(X + (size_t)(row0 + ai * HALF + m * 16) * 1024 + col0 + bj * HALF) = pack8(v); }
	v_lshlrev_b32_e32 v104, 16, v145
	v_and_b32_e32 v105, 0xffff0000, v145
	v_add_f32_e32 v94, v98, v94
	v_add_f32_e32 v98, v90, v102
	v_add_f32_e32 v90, v99, v95
	v_add_f32_e32 v95, v91, v103
	v_add_f32_e32 v91, v100, v96
	v_add_f32_e32 v96, v92, v104
	v_add_f32_e32 v92, v101, v97
	v_add_f32_e32 v93, v93, v105
	v_cvt_pk_bf16_f32 v90, v94, v90
	v_cvt_pk_bf16_f32 v91, v91, v92
	v_cvt_pk_bf16_f32 v92, v98, v95
	v_lshl_add_u64 v[94:95], s[18:19], 0, v[182:183]
	v_cvt_pk_bf16_f32 v93, v96, v93
	v_lshl_add_u64 v[94:95], v[94:95], 0, v[164:165]
	global_store_dwordx4 v[94:95], v[90:93], off
	v_lshlrev_b32_e32 v96, 16, v136
	v_and_b32_e32 v97, 0xffff0000, v136
	v_lshlrev_b32_e32 v90, 16, v134
	v_and_b32_e32 v91, 0xffff0000, v134
	v_lshlrev_b32_e32 v92, 16, v135
	v_and_b32_e32 v93, 0xffff0000, v135
	v_lshlrev_b32_e32 v98, 16, v137
	v_and_b32_e32 v99, 0xffff0000, v137
	v_add_f32_e32 v86, v86, v90
	v_add_f32_e32 v90, v78, v96
	v_add_f32_e32 v78, v87, v91
	v_add_f32_e32 v87, v79, v97
	v_add_f32_e32 v79, v88, v92
	v_add_f32_e32 v88, v80, v98
	v_add_f32_e32 v80, v89, v93
	v_add_f32_e32 v81, v81, v99
	v_cvt_pk_bf16_f32 v78, v86, v78
	v_cvt_pk_bf16_f32 v79, v79, v80
	v_cvt_pk_bf16_f32 v80, v90, v87
	v_cvt_pk_bf16_f32 v81, v88, v81
	global_store_dwordx4 v[94:95], v[78:81], off offset:256
	v_lshlrev_b32_e32 v86, 16, v140
	v_and_b32_e32 v87, 0xffff0000, v140
	v_lshlrev_b32_e32 v78, 16, v138
	v_and_b32_e32 v79, 0xffff0000, v138
	v_lshlrev_b32_e32 v80, 16, v139
	v_and_b32_e32 v81, 0xffff0000, v139
	v_lshlrev_b32_e32 v88, 16, v141
	v_and_b32_e32 v89, 0xffff0000, v141
	v_add_f32_e32 v78, v82, v78
	v_add_f32_e32 v82, v74, v86
	v_add_f32_e32 v74, v83, v79
	v_add_f32_e32 v79, v75, v87
	v_add_f32_e32 v75, v84, v80
	v_add_f32_e32 v80, v76, v88
	v_add_f32_e32 v76, v85, v81
	v_add_f32_e32 v77, v77, v89
	v_cvt_pk_bf16_f32 v74, v78, v74
	v_cvt_pk_bf16_f32 v75, v75, v76
	v_cvt_pk_bf16_f32 v76, v82, v79
	v_lshl_add_u64 v[78:79], s[18:19], 0, v[180:181]
	v_cvt_pk_bf16_f32 v77, v80, v77
	v_lshl_add_u64 v[78:79], v[78:79], 0, v[164:165]
	global_store_dwordx4 v[78:79], v[74:77], off
	v_lshlrev_b32_e32 v80, 16, v132
	v_and_b32_e32 v81, 0xffff0000, v132
	v_lshlrev_b32_e32 v74, 16, v130
	v_and_b32_e32 v75, 0xffff0000, v130
	v_lshlrev_b32_e32 v76, 16, v131
	v_and_b32_e32 v77, 0xffff0000, v131
	v_lshlrev_b32_e32 v82, 16, v133
	v_and_b32_e32 v83, 0xffff0000, v133
	v_add_f32_e32 v70, v70, v74
	v_add_f32_e32 v74, v66, v80
	v_add_f32_e32 v66, v71, v75
	v_add_f32_e32 v71, v67, v81
	v_add_f32_e32 v67, v72, v76
	v_add_f32_e32 v72, v68, v82
	v_add_f32_e32 v68, v73, v77
	v_add_f32_e32 v69, v69, v83
	v_lshl_add_u64 v[98:99], v[168:169], 0, s[82:83]
	v_cvt_pk_bf16_f32 v66, v70, v66
	v_cvt_pk_bf16_f32 v67, v67, v68
	v_cvt_pk_bf16_f32 v68, v74, v71
	v_cvt_pk_bf16_f32 v69, v72, v69
	global_store_dwordx4 v[78:79], v[66:69], off offset:256
	v_lshl_add_u64 v[70:71], v[166:167], 0, v[98:99]
	global_load_dwordx4 v[66:69], v[70:71], off
	s_nop 0
	global_load_dwordx4 v[70:73], v[70:71], off offset:256
	v_lshl_add_u64 v[100:101], v[168:169], 0, s[84:85]
	v_lshl_add_u64 v[78:79], v[166:167], 0, v[100:101]
	global_load_dwordx4 v[74:77], v[78:79], off
	s_nop 0
	global_load_dwordx4 v[78:81], v[78:79], off offset:256
	v_lshl_add_u64 v[102:103], v[168:169], 0, s[86:87]
	v_lshl_add_u64 v[86:87], v[166:167], 0, v[102:103]
	global_load_dwordx4 v[82:85], v[86:87], off
	s_nop 0
	global_load_dwordx4 v[86:89], v[86:87], off offset:256
	v_lshl_add_u64 v[104:105], v[168:169], 0, s[4:5]
	v_lshl_add_u64 v[94:95], v[166:167], 0, v[104:105]
	global_load_dwordx4 v[90:93], v[94:95], off
	s_nop 0
	global_load_dwordx4 v[94:97], v[94:95], off offset:256
	s_mov_b64 s[4:5], -1
	s_waitcnt vmcnt(7)
	v_lshlrev_b32_e32 v106, 16, v66
	v_and_b32_e32 v66, 0xffff0000, v66
	v_lshlrev_b32_e32 v107, 16, v67
	v_and_b32_e32 v67, 0xffff0000, v67
	v_lshlrev_b32_e32 v108, 16, v68
	v_and_b32_e32 v68, 0xffff0000, v68
	v_lshlrev_b32_e32 v109, 16, v69
	v_and_b32_e32 v69, 0xffff0000, v69
	v_add_f32_e32 v62, v62, v106
	v_add_f32_e32 v106, v58, v108
	v_add_f32_e32 v58, v63, v66
	v_add_f32_e32 v63, v59, v68
	v_add_f32_e32 v59, v64, v107
	v_add_f32_e32 v64, v60, v109
	v_add_f32_e32 v60, v65, v67
	v_add_f32_e32 v61, v61, v69
	v_cvt_pk_bf16_f32 v58, v62, v58
	v_cvt_pk_bf16_f32 v59, v59, v60
	v_cvt_pk_bf16_f32 v60, v106, v63
	v_lshl_add_u64 v[62:63], s[18:19], 0, v[98:99]
	v_cvt_pk_bf16_f32 v61, v64, v61
	v_lshl_add_u64 v[62:63], v[62:63], 0, v[164:165]
	global_store_dwordx4 v[62:63], v[58:61], off
	s_waitcnt vmcnt(7)
	v_lshlrev_b32_e32 v64, 16, v72
	v_and_b32_e32 v65, 0xffff0000, v72
	v_lshlrev_b32_e32 v58, 16, v70
	v_and_b32_e32 v59, 0xffff0000, v70
	v_lshlrev_b32_e32 v60, 16, v71
	v_and_b32_e32 v61, 0xffff0000, v71
	v_lshlrev_b32_e32 v66, 16, v73
	v_and_b32_e32 v67, 0xffff0000, v73
	v_add_f32_e32 v54, v54, v58
	v_add_f32_e32 v58, v46, v64
	v_add_f32_e32 v46, v55, v59
	v_add_f32_e32 v55, v47, v65
	v_add_f32_e32 v47, v56, v60
	v_add_f32_e32 v56, v48, v66
	v_add_f32_e32 v48, v57, v61
	v_add_f32_e32 v49, v49, v67
	v_cvt_pk_bf16_f32 v46, v54, v46
	v_cvt_pk_bf16_f32 v47, v47, v48
	v_cvt_pk_bf16_f32 v48, v58, v55
	v_cvt_pk_bf16_f32 v49, v56, v49
	global_store_dwordx4 v[62:63], v[46:49], off offset:256
	s_waitcnt vmcnt(7)
; DEV void unpack8(const u32x4 v, float (&f)[8]) { f[0] = bflo(v.x); f[1] = bfhi(v.x); f[2] = bflo(v.y); f[3] = bfhi(v.y); f[4] = bflo(v.z); f[5] = bfhi(v.z); f[6] = bflo(v.w); f[7] = bfhi(v.w); }
; DEV u32x4 pack8(const float (&f)[8]) { u32x4 w; w.x = cvt_pk_bf16(f[0], f[1]); w.y = cvt_pk_bf16(f[2], f[3]); w.z = cvt_pk_bf16(f[4], f[5]); w.w = cvt_pk_bf16(f[6], f[7]); return w; }
; #define PG8_BAR __builtin_amdgcn_s_barrier()
;     DEV bool operator()(f32x4 (&acc)[2][2][4][2], const Unit& u, int wr, int wc, int fr, int fq) const {
;     ...
;             for (int m = 0; m < 4; ++m)
; #pragma unroll
;                 for (int bj = 0; bj < 2; ++bj) { float v[8]; unpack8(old[m][bj], v);
; #pragma unroll
;                     for (int j = 0; j < 4; ++j) { v[j] += acc[ai][bj][m][0][j]; v[4 + j] += acc[ai][bj][m][1][j]; }
;                     *(u32x4*)(X + (size_t)(row0 + ai * HALF + m * 16) * 1024 + col0 + bj * HALF) = pack8(v); }
; template <bool ALIGN_EPI, class Epi, class Sched>
; DEV void gemm_phase(LAS unsigned char* lds, const Gemm g, const Sched& S, const Epi& E) {
;     ...
;         if (!has_next) break;
;         if (rst) {
; #pragma unroll
;         for (int a = 0; a < 2; ++a)
; #pragma unroll
;             for (int b = 0; b < 2; ++b)
; #pragma unroll
;                 for (int m = 0; m < 4; ++m)
; #pragma unroll
;                     for (int n = 0; n < 2; ++n) acc[a][b][m][n] = (f32x4){0.f, 0.f, 0.f, 0.f}; }
;         cur = nxt; cA = nA; cB = nB; ++ui;
;         if (ALIGN_EPI) { if (wr == 1) PG8_BAR; }
	v_lshlrev_b32_e32 v54, 16, v76
	v_and_b32_e32 v55, 0xffff0000, v76
	v_lshlrev_b32_e32 v46, 16, v74
	v_and_b32_e32 v47, 0xffff0000, v74
	v_lshlrev_b32_e32 v48, 16, v75
	v_and_b32_e32 v49, 0xffff0000, v75
	v_lshlrev_b32_e32 v56, 16, v77
	v_and_b32_e32 v57, 0xffff0000, v77
	v_add_f32_e32 v46, v50, v46
	v_add_f32_e32 v50, v42, v54
	v_add_f32_e32 v42, v51, v47
	v_add_f32_e32 v47, v43, v55
	v_add_f32_e32 v43, v52, v48
	v_add_f32_e32 v48, v44, v56
	v_add_f32_e32 v44, v53, v49
	v_add_f32_e32 v45, v45, v57
	v_cvt_pk_bf16_f32 v42, v46, v42
	v_cvt_pk_bf16_f32 v43, v43, v44
	v_cvt_pk_bf16_f32 v44, v50, v47
	v_lshl_add_u64 v[46:47], s[18:19], 0, v[100:101]
	v_cvt_pk_bf16_f32 v45, v48, v45
	v_lshl_add_u64 v[46:47], v[46:47], 0, v[164:165]
	global_store_dwordx4 v[46:47], v[42:45], off
	s_waitcnt vmcnt(7)
	v_lshlrev_b32_e32 v48, 16, v80
	v_and_b32_e32 v49, 0xffff0000, v80
	v_lshlrev_b32_e32 v42, 16, v78
	v_and_b32_e32 v43, 0xffff0000, v78
	v_lshlrev_b32_e32 v44, 16, v79
	v_and_b32_e32 v45, 0xffff0000, v79
	v_lshlrev_b32_e32 v50, 16, v81
	v_and_b32_e32 v51, 0xffff0000, v81
	v_add_f32_e32 v38, v38, v42
	v_add_f32_e32 v42, v30, v48
	v_add_f32_e32 v30, v39, v43
	v_add_f32_e32 v39, v31, v49
	v_add_f32_e32 v31, v40, v44
	v_add_f32_e32 v40, v32, v50
	v_add_f32_e32 v32, v41, v45
	v_add_f32_e32 v33, v33, v51
	v_cvt_pk_bf16_f32 v30, v38, v30
	v_cvt_pk_bf16_f32 v31, v31, v32
	v_cvt_pk_bf16_f32 v32, v42, v39
	v_cvt_pk_bf16_f32 v33, v40, v33
	global_store_dwordx4 v[46:47], v[30:33], off offset:256
	s_waitcnt vmcnt(7)
	v_lshlrev_b32_e32 v38, 16, v84
	v_and_b32_e32 v39, 0xffff0000, v84
	v_lshlrev_b32_e32 v30, 16, v82
	v_and_b32_e32 v31, 0xffff0000, v82
	v_lshlrev_b32_e32 v32, 16, v83
	v_and_b32_e32 v33, 0xffff0000, v83
	v_lshlrev_b32_e32 v40, 16, v85
	v_and_b32_e32 v41, 0xffff0000, v85
	v_add_f32_e32 v30, v34, v30
	v_add_f32_e32 v34, v26, v38
	v_add_f32_e32 v26, v35, v31
	v_add_f32_e32 v31, v27, v39
	v_add_f32_e32 v27, v36, v32
	v_add_f32_e32 v32, v28, v40
	v_add_f32_e32 v28, v37, v33
	v_add_f32_e32 v29, v29, v41
	v_cvt_pk_bf16_f32 v26, v30, v26
	v_cvt_pk_bf16_f32 v27, v27, v28
	v_cvt_pk_bf16_f32 v28, v34, v31
	v_lshl_add_u64 v[30:31], s[18:19], 0, v[102:103]
	v_cvt_pk_bf16_f32 v29, v32, v29
	v_lshl_add_u64 v[30:31], v[30:31], 0, v[164:165]
	global_store_dwordx4 v[30:31], v[26:29], off
	s_waitcnt vmcnt(7)
	v_lshlrev_b32_e32 v32, 16, v88
	v_and_b32_e32 v33, 0xffff0000, v88
	v_lshlrev_b32_e32 v26, 16, v86
	v_and_b32_e32 v27, 0xffff0000, v86
	v_lshlrev_b32_e32 v28, 16, v87
	v_and_b32_e32 v29, 0xffff0000, v87
	v_lshlrev_b32_e32 v34, 16, v89
	v_and_b32_e32 v35, 0xffff0000, v89
	v_add_f32_e32 v22, v22, v26
	v_add_f32_e32 v26, v14, v32
	v_add_f32_e32 v14, v23, v27
	v_add_f32_e32 v23, v15, v33
	v_add_f32_e32 v15, v24, v28
	v_add_f32_e32 v24, v16, v34
	v_add_f32_e32 v16, v25, v29
	v_add_f32_e32 v17, v17, v35
	v_cvt_pk_bf16_f32 v14, v22, v14
	v_cvt_pk_bf16_f32 v15, v15, v16
	v_cvt_pk_bf16_f32 v16, v26, v23
	v_cvt_pk_bf16_f32 v17, v24, v17
	global_store_dwordx4 v[30:31], v[14:17], off offset:256
	s_waitcnt vmcnt(7)
	v_lshlrev_b32_e32 v22, 16, v92
	v_and_b32_e32 v23, 0xffff0000, v92
	v_lshlrev_b32_e32 v14, 16, v90
	v_and_b32_e32 v15, 0xffff0000, v90
	v_lshlrev_b32_e32 v16, 16, v91
	v_and_b32_e32 v17, 0xffff0000, v91
	v_lshlrev_b32_e32 v24, 16, v93
	v_and_b32_e32 v25, 0xffff0000, v93
	v_add_f32_e32 v14, v18, v14
	v_add_f32_e32 v18, v10, v22
	v_add_f32_e32 v10, v19, v15
	v_add_f32_e32 v15, v11, v23
	v_add_f32_e32 v11, v20, v16
	v_add_f32_e32 v16, v12, v24
	v_add_f32_e32 v12, v21, v17
	v_add_f32_e32 v13, v13, v25
	v_cvt_pk_bf16_f32 v10, v14, v10
	v_cvt_pk_bf16_f32 v11, v11, v12
	v_cvt_pk_bf16_f32 v12, v18, v15
	v_lshl_add_u64 v[14:15], s[18:19], 0, v[104:105]
	v_cvt_pk_bf16_f32 v13, v16, v13
	v_lshl_add_u64 v[14:15], v[14:15], 0, v[164:165]
	global_store_dwordx4 v[14:15], v[10:13], off
	s_waitcnt vmcnt(7)
	v_lshlrev_b32_e32 v16, 16, v96
	v_and_b32_e32 v17, 0xffff0000, v96
	v_lshlrev_b32_e32 v10, 16, v94
	v_and_b32_e32 v11, 0xffff0000, v94
	v_lshlrev_b32_e32 v12, 16, v95
	v_and_b32_e32 v13, 0xffff0000, v95
	v_lshlrev_b32_e32 v18, 16, v97
	v_and_b32_e32 v19, 0xffff0000, v97
	v_add_f32_e32 v6, v6, v10
	v_add_f32_e32 v10, v2, v16
	v_add_f32_e32 v2, v7, v11
	v_add_f32_e32 v7, v3, v17
	v_add_f32_e32 v3, v8, v12
	v_add_f32_e32 v8, v4, v18
	v_add_f32_e32 v4, v9, v13
	v_add_f32_e32 v5, v5, v19
	v_cvt_pk_bf16_f32 v2, v6, v2
	v_cvt_pk_bf16_f32 v3, v3, v4
	v_cvt_pk_bf16_f32 v4, v10, v7
	v_cvt_pk_bf16_f32 v5, v8, v5
	global_store_dwordx4 v[14:15], v[2:5], off offset:256
	s_cbranch_vccnz .LBB0_476
	s_andn2_b64 vcc, exec, s[44:45]
	s_cbranch_vccnz .LBB0_475
	s_barrier
	s_branch .LBB0_475
